# prologue modulation GEMV: 16 weight-row loads in flight per wave with rolling refills and counted waits, LDS operand reads double-buffered
# baseline (speedup 1.0000x reference)
.LBB0_408:
	v_mov_b32_e32 v64, v56
	v_mov_b32_e32 v65, v57
	v_mov_b32_e32 v66, v51
	global_load_dword v0, v[64:65], off
	v_lshl_add_u64 v[64:65], v[64:65], 0, s[44:45]
	global_load_dword v1, v[64:65], off
	v_lshl_add_u64 v[64:65], v[64:65], 0, s[44:45]
	global_load_dword v2, v[64:65], off
	v_lshl_add_u64 v[64:65], v[64:65], 0, s[44:45]
	global_load_dword v3, v[64:65], off
	v_lshl_add_u64 v[64:65], v[64:65], 0, s[44:45]
	global_load_dword v4, v[64:65], off
	v_lshl_add_u64 v[64:65], v[64:65], 0, s[44:45]
	global_load_dword v5, v[64:65], off
	v_lshl_add_u64 v[64:65], v[64:65], 0, s[44:45]
	global_load_dword v6, v[64:65], off
	v_lshl_add_u64 v[64:65], v[64:65], 0, s[44:45]
	global_load_dword v7, v[64:65], off
	v_lshl_add_u64 v[64:65], v[64:65], 0, s[44:45]
	global_load_dword v8, v[64:65], off
	v_lshl_add_u64 v[64:65], v[64:65], 0, s[44:45]
	global_load_dword v9, v[64:65], off
	v_lshl_add_u64 v[64:65], v[64:65], 0, s[44:45]
	global_load_dword v10, v[64:65], off
	v_lshl_add_u64 v[64:65], v[64:65], 0, s[44:45]
	global_load_dword v11, v[64:65], off
	v_lshl_add_u64 v[64:65], v[64:65], 0, s[44:45]
	global_load_dword v12, v[64:65], off
	v_lshl_add_u64 v[64:65], v[64:65], 0, s[44:45]
	global_load_dword v13, v[64:65], off
	v_lshl_add_u64 v[64:65], v[64:65], 0, s[44:45]
	global_load_dword v14, v[64:65], off
	v_lshl_add_u64 v[64:65], v[64:65], 0, s[44:45]
	global_load_dword v15, v[64:65], off
	v_lshl_add_u64 v[64:65], v[64:65], 0, s[44:45]
	ds_read_b128 v[96:99], v66 offset:0
	ds_read_b128 v[100:103], v66 offset:4096
	ds_read_b128 v[104:107], v66 offset:8192
	ds_read_b128 v[108:111], v66 offset:12288
	ds_read_b128 v[112:115], v66 offset:16384
	ds_read_b128 v[116:119], v66 offset:20480
	ds_read_b128 v[120:123], v66 offset:24576
	ds_read_b128 v[124:127], v66 offset:28672
	s_mov_b32 s24, 0
.Lmods_it:
	ds_read_b128 v[128:131], v66 offset:16
	ds_read_b128 v[132:135], v66 offset:4112
	ds_read_b128 v[136:139], v66 offset:8208
	ds_read_b128 v[140:143], v66 offset:12304
	ds_read_b128 v[144:147], v66 offset:16400
	ds_read_b128 v[148:151], v66 offset:20496
	ds_read_b128 v[152:155], v66 offset:24592
	ds_read_b128 v[156:159], v66 offset:28688
	s_waitcnt lgkmcnt(8)
	s_waitcnt vmcnt(12)
	v_fmac_f32_e32 v63, v96, v0
	v_fmac_f32_e32 v62, v100, v0
	v_fmac_f32_e32 v61, v104, v0
	v_fmac_f32_e32 v60, v108, v0
	v_fmac_f32_e32 v59, v112, v0
	v_fmac_f32_e32 v58, v116, v0
	v_fmac_f32_e32 v17, v120, v0
	v_fmac_f32_e32 v16, v124, v0
	v_fmac_f32_e32 v63, v97, v1
	v_fmac_f32_e32 v62, v101, v1
	v_fmac_f32_e32 v61, v105, v1
	v_fmac_f32_e32 v60, v109, v1
	v_fmac_f32_e32 v59, v113, v1
	v_fmac_f32_e32 v58, v117, v1
	v_fmac_f32_e32 v17, v121, v1
	v_fmac_f32_e32 v16, v125, v1
	v_fmac_f32_e32 v63, v98, v2
	v_fmac_f32_e32 v62, v102, v2
	v_fmac_f32_e32 v61, v106, v2
	v_fmac_f32_e32 v60, v110, v2
	v_fmac_f32_e32 v59, v114, v2
	v_fmac_f32_e32 v58, v118, v2
	v_fmac_f32_e32 v17, v122, v2
	v_fmac_f32_e32 v16, v126, v2
	v_fmac_f32_e32 v63, v99, v3
	v_fmac_f32_e32 v62, v103, v3
	v_fmac_f32_e32 v61, v107, v3
	v_fmac_f32_e32 v60, v111, v3
	v_fmac_f32_e32 v59, v115, v3
	v_fmac_f32_e32 v58, v119, v3
	v_fmac_f32_e32 v17, v123, v3
	v_fmac_f32_e32 v16, v127, v3
	global_load_dword v0, v[64:65], off
	v_lshl_add_u64 v[64:65], v[64:65], 0, s[44:45]
	global_load_dword v1, v[64:65], off
	v_lshl_add_u64 v[64:65], v[64:65], 0, s[44:45]
	global_load_dword v2, v[64:65], off
	v_lshl_add_u64 v[64:65], v[64:65], 0, s[44:45]
	global_load_dword v3, v[64:65], off
	v_lshl_add_u64 v[64:65], v[64:65], 0, s[44:45]
	ds_read_b128 v[96:99], v66 offset:32
	ds_read_b128 v[100:103], v66 offset:4128
	ds_read_b128 v[104:107], v66 offset:8224
	ds_read_b128 v[108:111], v66 offset:12320
	ds_read_b128 v[112:115], v66 offset:16416
	ds_read_b128 v[116:119], v66 offset:20512
	ds_read_b128 v[120:123], v66 offset:24608
	ds_read_b128 v[124:127], v66 offset:28704
	s_waitcnt lgkmcnt(8)
	s_waitcnt vmcnt(12)
	v_fmac_f32_e32 v63, v128, v4
	v_fmac_f32_e32 v62, v132, v4
	v_fmac_f32_e32 v61, v136, v4
	v_fmac_f32_e32 v60, v140, v4
	v_fmac_f32_e32 v59, v144, v4
	v_fmac_f32_e32 v58, v148, v4
	v_fmac_f32_e32 v17, v152, v4
	v_fmac_f32_e32 v16, v156, v4
	v_fmac_f32_e32 v63, v129, v5
	v_fmac_f32_e32 v62, v133, v5
	v_fmac_f32_e32 v61, v137, v5
	v_fmac_f32_e32 v60, v141, v5
	v_fmac_f32_e32 v59, v145, v5
	v_fmac_f32_e32 v58, v149, v5
	v_fmac_f32_e32 v17, v153, v5
	v_fmac_f32_e32 v16, v157, v5
	v_fmac_f32_e32 v63, v130, v6
	v_fmac_f32_e32 v62, v134, v6
	v_fmac_f32_e32 v61, v138, v6
	v_fmac_f32_e32 v60, v142, v6
	v_fmac_f32_e32 v59, v146, v6
	v_fmac_f32_e32 v58, v150, v6
	v_fmac_f32_e32 v17, v154, v6
	v_fmac_f32_e32 v16, v158, v6
	v_fmac_f32_e32 v63, v131, v7
	v_fmac_f32_e32 v62, v135, v7
	v_fmac_f32_e32 v61, v139, v7
	v_fmac_f32_e32 v60, v143, v7
	v_fmac_f32_e32 v59, v147, v7
	v_fmac_f32_e32 v58, v151, v7
	v_fmac_f32_e32 v17, v155, v7
	v_fmac_f32_e32 v16, v159, v7
	global_load_dword v4, v[64:65], off
	v_lshl_add_u64 v[64:65], v[64:65], 0, s[44:45]
	global_load_dword v5, v[64:65], off
	v_lshl_add_u64 v[64:65], v[64:65], 0, s[44:45]
	global_load_dword v6, v[64:65], off
	v_lshl_add_u64 v[64:65], v[64:65], 0, s[44:45]
	global_load_dword v7, v[64:65], off
	v_lshl_add_u64 v[64:65], v[64:65], 0, s[44:45]
	ds_read_b128 v[128:131], v66 offset:48
	ds_read_b128 v[132:135], v66 offset:4144
	ds_read_b128 v[136:139], v66 offset:8240
	ds_read_b128 v[140:143], v66 offset:12336
	ds_read_b128 v[144:147], v66 offset:16432
	ds_read_b128 v[148:151], v66 offset:20528
	ds_read_b128 v[152:155], v66 offset:24624
	ds_read_b128 v[156:159], v66 offset:28720
	s_waitcnt lgkmcnt(8)
	s_waitcnt vmcnt(12)
	v_fmac_f32_e32 v63, v96, v8
	v_fmac_f32_e32 v62, v100, v8
	v_fmac_f32_e32 v61, v104, v8
	v_fmac_f32_e32 v60, v108, v8
	v_fmac_f32_e32 v59, v112, v8
	v_fmac_f32_e32 v58, v116, v8
	v_fmac_f32_e32 v17, v120, v8
	v_fmac_f32_e32 v16, v124, v8
	v_fmac_f32_e32 v63, v97, v9
	v_fmac_f32_e32 v62, v101, v9
	v_fmac_f32_e32 v61, v105, v9
	v_fmac_f32_e32 v60, v109, v9
	v_fmac_f32_e32 v59, v113, v9
	v_fmac_f32_e32 v58, v117, v9
	v_fmac_f32_e32 v17, v121, v9
	v_fmac_f32_e32 v16, v125, v9
	v_fmac_f32_e32 v63, v98, v10
	v_fmac_f32_e32 v62, v102, v10
	v_fmac_f32_e32 v61, v106, v10
	v_fmac_f32_e32 v60, v110, v10
	v_fmac_f32_e32 v59, v114, v10
	v_fmac_f32_e32 v58, v118, v10
	v_fmac_f32_e32 v17, v122, v10
	v_fmac_f32_e32 v16, v126, v10
	v_fmac_f32_e32 v63, v99, v11
	v_fmac_f32_e32 v62, v103, v11
	v_fmac_f32_e32 v61, v107, v11
	v_fmac_f32_e32 v60, v111, v11
	v_fmac_f32_e32 v59, v115, v11
	v_fmac_f32_e32 v58, v119, v11
	v_fmac_f32_e32 v17, v123, v11
	v_fmac_f32_e32 v16, v127, v11
	global_load_dword v8, v[64:65], off
	v_lshl_add_u64 v[64:65], v[64:65], 0, s[44:45]
	global_load_dword v9, v[64:65], off
	v_lshl_add_u64 v[64:65], v[64:65], 0, s[44:45]
	global_load_dword v10, v[64:65], off
	v_lshl_add_u64 v[64:65], v[64:65], 0, s[44:45]
	global_load_dword v11, v[64:65], off
	v_lshl_add_u64 v[64:65], v[64:65], 0, s[44:45]
	v_add_u32_e32 v66, 64, v66
	ds_read_b128 v[96:99], v66 offset:0
	ds_read_b128 v[100:103], v66 offset:4096
	ds_read_b128 v[104:107], v66 offset:8192
	ds_read_b128 v[108:111], v66 offset:12288
	ds_read_b128 v[112:115], v66 offset:16384
	ds_read_b128 v[116:119], v66 offset:20480
	ds_read_b128 v[120:123], v66 offset:24576
	ds_read_b128 v[124:127], v66 offset:28672
	s_waitcnt lgkmcnt(8)
	s_waitcnt vmcnt(12)
	v_fmac_f32_e32 v63, v128, v12
	v_fmac_f32_e32 v62, v132, v12
	v_fmac_f32_e32 v61, v136, v12
	v_fmac_f32_e32 v60, v140, v12
	v_fmac_f32_e32 v59, v144, v12
	v_fmac_f32_e32 v58, v148, v12
	v_fmac_f32_e32 v17, v152, v12
	v_fmac_f32_e32 v16, v156, v12
	v_fmac_f32_e32 v63, v129, v13
	v_fmac_f32_e32 v62, v133, v13
	v_fmac_f32_e32 v61, v137, v13
	v_fmac_f32_e32 v60, v141, v13
	v_fmac_f32_e32 v59, v145, v13
	v_fmac_f32_e32 v58, v149, v13
	v_fmac_f32_e32 v17, v153, v13
	v_fmac_f32_e32 v16, v157, v13
	v_fmac_f32_e32 v63, v130, v14
	v_fmac_f32_e32 v62, v134, v14
	v_fmac_f32_e32 v61, v138, v14
	v_fmac_f32_e32 v60, v142, v14
	v_fmac_f32_e32 v59, v146, v14
	v_fmac_f32_e32 v58, v150, v14
	v_fmac_f32_e32 v17, v154, v14
	v_fmac_f32_e32 v16, v158, v14
	v_fmac_f32_e32 v63, v131, v15
	v_fmac_f32_e32 v62, v135, v15
	v_fmac_f32_e32 v61, v139, v15
	v_fmac_f32_e32 v60, v143, v15
	v_fmac_f32_e32 v59, v147, v15
	v_fmac_f32_e32 v58, v151, v15
	v_fmac_f32_e32 v17, v155, v15
	v_fmac_f32_e32 v16, v159, v15
	global_load_dword v12, v[64:65], off
	v_lshl_add_u64 v[64:65], v[64:65], 0, s[44:45]
	global_load_dword v13, v[64:65], off
	v_lshl_add_u64 v[64:65], v[64:65], 0, s[44:45]
	global_load_dword v14, v[64:65], off
	v_lshl_add_u64 v[64:65], v[64:65], 0, s[44:45]
	global_load_dword v15, v[64:65], off
	v_lshl_add_u64 v[64:65], v[64:65], 0, s[44:45]
	s_add_i32 s24, s24, 1
	s_cmp_eq_u32 s24, 7
	s_cbranch_scc0 .Lmods_it
	ds_read_b128 v[128:131], v66 offset:16
	ds_read_b128 v[132:135], v66 offset:4112
	ds_read_b128 v[136:139], v66 offset:8208
	ds_read_b128 v[140:143], v66 offset:12304
	ds_read_b128 v[144:147], v66 offset:16400
	ds_read_b128 v[148:151], v66 offset:20496
	ds_read_b128 v[152:155], v66 offset:24592
	ds_read_b128 v[156:159], v66 offset:28688
	s_waitcnt lgkmcnt(8)
	s_waitcnt vmcnt(12)
	v_fmac_f32_e32 v63, v96, v0
	v_fmac_f32_e32 v62, v100, v0
	v_fmac_f32_e32 v61, v104, v0
	v_fmac_f32_e32 v60, v108, v0
	v_fmac_f32_e32 v59, v112, v0
	v_fmac_f32_e32 v58, v116, v0
	v_fmac_f32_e32 v17, v120, v0
	v_fmac_f32_e32 v16, v124, v0
	v_fmac_f32_e32 v63, v97, v1
	v_fmac_f32_e32 v62, v101, v1
	v_fmac_f32_e32 v61, v105, v1
	v_fmac_f32_e32 v60, v109, v1
	v_fmac_f32_e32 v59, v113, v1
	v_fmac_f32_e32 v58, v117, v1
	v_fmac_f32_e32 v17, v121, v1
	v_fmac_f32_e32 v16, v125, v1
	v_fmac_f32_e32 v63, v98, v2
	v_fmac_f32_e32 v62, v102, v2
	v_fmac_f32_e32 v61, v106, v2
	v_fmac_f32_e32 v60, v110, v2
	v_fmac_f32_e32 v59, v114, v2
	v_fmac_f32_e32 v58, v118, v2
	v_fmac_f32_e32 v17, v122, v2
	v_fmac_f32_e32 v16, v126, v2
	v_fmac_f32_e32 v63, v99, v3
	v_fmac_f32_e32 v62, v103, v3
	v_fmac_f32_e32 v61, v107, v3
	v_fmac_f32_e32 v60, v111, v3
	v_fmac_f32_e32 v59, v115, v3
	v_fmac_f32_e32 v58, v119, v3
	v_fmac_f32_e32 v17, v123, v3
	v_fmac_f32_e32 v16, v127, v3
	ds_read_b128 v[96:99], v66 offset:32
	ds_read_b128 v[100:103], v66 offset:4128
	ds_read_b128 v[104:107], v66 offset:8224
	ds_read_b128 v[108:111], v66 offset:12320
	ds_read_b128 v[112:115], v66 offset:16416
	ds_read_b128 v[116:119], v66 offset:20512
	ds_read_b128 v[120:123], v66 offset:24608
	ds_read_b128 v[124:127], v66 offset:28704
	s_waitcnt lgkmcnt(8)
	s_waitcnt vmcnt(8)
	v_fmac_f32_e32 v63, v128, v4
	v_fmac_f32_e32 v62, v132, v4
	v_fmac_f32_e32 v61, v136, v4
	v_fmac_f32_e32 v60, v140, v4
	v_fmac_f32_e32 v59, v144, v4
	v_fmac_f32_e32 v58, v148, v4
	v_fmac_f32_e32 v17, v152, v4
	v_fmac_f32_e32 v16, v156, v4
	v_fmac_f32_e32 v63, v129, v5
	v_fmac_f32_e32 v62, v133, v5
	v_fmac_f32_e32 v61, v137, v5
	v_fmac_f32_e32 v60, v141, v5
	v_fmac_f32_e32 v59, v145, v5
	v_fmac_f32_e32 v58, v149, v5
	v_fmac_f32_e32 v17, v153, v5
	v_fmac_f32_e32 v16, v157, v5
	v_fmac_f32_e32 v63, v130, v6
	v_fmac_f32_e32 v62, v134, v6
	v_fmac_f32_e32 v61, v138, v6
	v_fmac_f32_e32 v60, v142, v6
	v_fmac_f32_e32 v59, v146, v6
	v_fmac_f32_e32 v58, v150, v6
	v_fmac_f32_e32 v17, v154, v6
	v_fmac_f32_e32 v16, v158, v6
	v_fmac_f32_e32 v63, v131, v7
	v_fmac_f32_e32 v62, v135, v7
	v_fmac_f32_e32 v61, v139, v7
	v_fmac_f32_e32 v60, v143, v7
	v_fmac_f32_e32 v59, v147, v7
	v_fmac_f32_e32 v58, v151, v7
	v_fmac_f32_e32 v17, v155, v7
	v_fmac_f32_e32 v16, v159, v7
	ds_read_b128 v[128:131], v66 offset:48
	ds_read_b128 v[132:135], v66 offset:4144
	ds_read_b128 v[136:139], v66 offset:8240
	ds_read_b128 v[140:143], v66 offset:12336
	ds_read_b128 v[144:147], v66 offset:16432
	ds_read_b128 v[148:151], v66 offset:20528
	ds_read_b128 v[152:155], v66 offset:24624
	ds_read_b128 v[156:159], v66 offset:28720
	s_waitcnt lgkmcnt(8)
	s_waitcnt vmcnt(4)
	v_fmac_f32_e32 v63, v96, v8
	v_fmac_f32_e32 v62, v100, v8
	v_fmac_f32_e32 v61, v104, v8
	v_fmac_f32_e32 v60, v108, v8
	v_fmac_f32_e32 v59, v112, v8
	v_fmac_f32_e32 v58, v116, v8
	v_fmac_f32_e32 v17, v120, v8
	v_fmac_f32_e32 v16, v124, v8
	v_fmac_f32_e32 v63, v97, v9
	v_fmac_f32_e32 v62, v101, v9
	v_fmac_f32_e32 v61, v105, v9
	v_fmac_f32_e32 v60, v109, v9
	v_fmac_f32_e32 v59, v113, v9
	v_fmac_f32_e32 v58, v117, v9
	v_fmac_f32_e32 v17, v121, v9
	v_fmac_f32_e32 v16, v125, v9
	v_fmac_f32_e32 v63, v98, v10
	v_fmac_f32_e32 v62, v102, v10
	v_fmac_f32_e32 v61, v106, v10
	v_fmac_f32_e32 v60, v110, v10
	v_fmac_f32_e32 v59, v114, v10
	v_fmac_f32_e32 v58, v118, v10
	v_fmac_f32_e32 v17, v122, v10
	v_fmac_f32_e32 v16, v126, v10
	v_fmac_f32_e32 v63, v99, v11
	v_fmac_f32_e32 v62, v103, v11
	v_fmac_f32_e32 v61, v107, v11
	v_fmac_f32_e32 v60, v111, v11
	v_fmac_f32_e32 v59, v115, v11
	v_fmac_f32_e32 v58, v119, v11
	v_fmac_f32_e32 v17, v123, v11
	v_fmac_f32_e32 v16, v127, v11
	v_add_u32_e32 v66, 64, v66
	ds_read_b128 v[96:99], v66 offset:0
	ds_read_b128 v[100:103], v66 offset:4096
	ds_read_b128 v[104:107], v66 offset:8192
	ds_read_b128 v[108:111], v66 offset:12288
	ds_read_b128 v[112:115], v66 offset:16384
	ds_read_b128 v[116:119], v66 offset:20480
	ds_read_b128 v[120:123], v66 offset:24576
	ds_read_b128 v[124:127], v66 offset:28672
	s_waitcnt lgkmcnt(8)
	s_waitcnt vmcnt(0)
	v_fmac_f32_e32 v63, v128, v12
	v_fmac_f32_e32 v62, v132, v12
	v_fmac_f32_e32 v61, v136, v12
	v_fmac_f32_e32 v60, v140, v12
	v_fmac_f32_e32 v59, v144, v12
	v_fmac_f32_e32 v58, v148, v12
	v_fmac_f32_e32 v17, v152, v12
	v_fmac_f32_e32 v16, v156, v12
	v_fmac_f32_e32 v63, v129, v13
	v_fmac_f32_e32 v62, v133, v13
	v_fmac_f32_e32 v61, v137, v13
	v_fmac_f32_e32 v60, v141, v13
	v_fmac_f32_e32 v59, v145, v13
	v_fmac_f32_e32 v58, v149, v13
	v_fmac_f32_e32 v17, v153, v13
	v_fmac_f32_e32 v16, v157, v13
	v_fmac_f32_e32 v63, v130, v14
	v_fmac_f32_e32 v62, v134, v14
	v_fmac_f32_e32 v61, v138, v14
	v_fmac_f32_e32 v60, v142, v14
	v_fmac_f32_e32 v59, v146, v14
	v_fmac_f32_e32 v58, v150, v14
	v_fmac_f32_e32 v17, v154, v14
	v_fmac_f32_e32 v16, v158, v14
	v_fmac_f32_e32 v63, v131, v15
	v_fmac_f32_e32 v62, v135, v15
	v_fmac_f32_e32 v61, v139, v15
	v_fmac_f32_e32 v60, v143, v15
	v_fmac_f32_e32 v59, v147, v15
	v_fmac_f32_e32 v58, v151, v15
	v_fmac_f32_e32 v17, v155, v15
	v_fmac_f32_e32 v16, v159, v15
	v_add_u32_e32 v0, s0, v50
	v_ashrrev_i32_e32 v1, 31, v0
	v_lshl_add_u64 v[0:1], v[0:1], 2, s[40:41]
	ds_write2st64_b32 v53, v63, v62 offset0:128 offset1:129
	ds_write2st64_b32 v53, v61, v60 offset0:130 offset1:131
	ds_write2st64_b32 v53, v59, v58 offset0:132 offset1:133
	ds_write2st64_b32 v53, v17, v16 offset0:134 offset1:135
	s_waitcnt lgkmcnt(0)
	s_barrier
	global_load_dword v10, v[0:1], off
	ds_read2st64_b32 v[0:1], v55 offset0:128 offset1:136
	ds_read2st64_b32 v[2:3], v55 offset0:144 offset1:152
	ds_read2st64_b32 v[4:5], v55 offset0:160 offset1:168
	ds_read2st64_b32 v[6:7], v55 offset0:176 offset1:184
	v_mad_i64_i32 v[8:9], s[24:25], s42, v52, 0
	v_lshl_add_u64 v[8:9], v[8:9], 2, s[38:39]
	s_add_i32 s46, s46, 64
	v_lshl_add_u64 v[8:9], s[0:1], 2, v[8:9]
	s_lshr_b32 vcc_lo, s46, 6
	s_cmp_lg_u32 vcc_lo, 4
	v_lshl_add_u64 v[8:9], v[8:9], 0, v[164:165]
	s_waitcnt vmcnt(0) lgkmcnt(3)
	v_add_f32_e32 v0, v10, v0
	v_add_f32_e32 v0, v0, v1
	s_waitcnt lgkmcnt(2)
	v_add_f32_e32 v0, v0, v2
	v_add_f32_e32 v0, v0, v3
	s_waitcnt lgkmcnt(1)
	v_add_f32_e32 v0, v0, v4
	v_add_f32_e32 v0, v0, v5
	s_waitcnt lgkmcnt(0)
	v_add_f32_e32 v0, v0, v6
	v_add_f32_e32 v0, v0, v7
	global_store_dword v[8:9], v0, off
	s_barrier
	s_cbranch_scc0 .LBB0_403
